# XCD barrier: wave 1 issues the CU L1 invalidate right after the drain barrier, concurrently with wave 0's arrival protocol
# baseline (speedup 1.0000x reference)
.LBB0_78:
	s_waitcnt vmcnt(0)
	s_barrier
	v_readfirstlane_b32 s98, v192
	s_nop 3
	s_lshr_b32 s98, s98, 6
	s_cmp_lg_u32 s98, 1
	s_cbranch_scc1 .Lxb_w1_0
	buffer_inv sc1
	s_waitcnt vmcnt(0)
.Lxb_w1_0:
	s_mov_b64 s[2:3], exec
	v_readlane_b32 s4, v254, 39
	v_readlane_b32 s5, v254, 40
	s_and_b64 s[4:5], s[2:3], s[4:5]
	s_mov_b64 exec, s[4:5]
	s_cbranch_execz .LBB0_130
	s_add_i32 s1, 0, 0x23ff0
	v_mov_b32_e32 v0, s1
	s_waitcnt vmcnt(0) expcnt(0) lgkmcnt(0)
	ds_read_b32 v2, v0
	s_add_i32 s1, 0, 0x23ff4
	v_mov_b32_e32 v0, s1
	ds_read_b32 v0, v0
	s_waitcnt lgkmcnt(1)
	v_cmp_ne_u32_e32 vcc, 0, v2
	s_cbranch_vccnz .LBB0_94
	s_add_u32 s4, s78, 0x80200
	s_addc_u32 s5, s79, 0
	s_add_u32 s6, s78, 0x80400
	s_addc_u32 s7, s79, 0
	s_add_u32 s8, s78, 0x80500
	s_addc_u32 s9, s79, 0
	s_add_u32 s10, s78, 0x80600
	s_addc_u32 s11, s79, 0
	s_add_u32 s14, s78, 0x80700
	s_addc_u32 s15, s79, 0
	s_add_u32 s16, s78, 0x80800
	s_addc_u32 s17, s79, 0
	s_add_u32 s18, s78, 0x80900
	s_addc_u32 s19, s79, 0
	s_add_u32 s20, s78, 0x80a00
	s_addc_u32 s21, s79, 0
	s_add_u32 s22, s78, 0x80b00
	s_addc_u32 s23, s79, 0
	s_add_u32 s24, s78, 0x80c00
	s_addc_u32 s25, s79, 0
	s_add_u32 s26, s78, 0x80d00
	s_addc_u32 s27, s79, 0
	s_add_u32 s28, s78, 0x80e00
	s_addc_u32 s29, s79, 0
	s_add_u32 s30, s78, 0x80f00
	s_addc_u32 s31, s79, 0
	s_add_u32 s34, s78, 0x81000
	s_addc_u32 s35, s79, 0
	s_add_u32 s36, s78, 0x81100
	s_addc_u32 s37, s79, 0
	s_add_u32 s38, s78, 0x81200
	v_readlane_b32 s1, v254, 1
	s_addc_u32 s39, s79, 0
	s_mul_i32 s1, s51, s1
	s_add_u32 s40, s78, 0x81300
	s_mul_i32 s1, s1, s50
	s_addc_u32 s41, s79, 0
	s_mov_b32 s12, 1
	v_mov_b32_e32 v16, 0
	s_branch .LBB0_82

.LBB0_199:
	s_waitcnt vmcnt(0)
	s_waitcnt vmcnt(0) lgkmcnt(0)
	s_barrier
	v_readfirstlane_b32 s98, v192
	s_nop 3
	s_lshr_b32 s98, s98, 6
	s_cmp_lg_u32 s98, 1
	s_cbranch_scc1 .Lxb_w1_1
	buffer_inv sc1
	s_waitcnt vmcnt(0)
.Lxb_w1_1:
	s_mov_b64 s[2:3], exec
	v_readlane_b32 s4, v254, 39
	v_readlane_b32 s5, v254, 40
	s_and_b64 s[4:5], s[2:3], s[4:5]
	s_mov_b64 exec, s[4:5]
	s_cbranch_execz .LBB0_251
	s_add_i32 s1, 0, 0x23ff0
	v_mov_b32_e32 v0, s1
	s_waitcnt vmcnt(0) expcnt(0) lgkmcnt(0)
	ds_read_b32 v2, v0
	s_add_i32 s1, 0, 0x23ff4
	v_mov_b32_e32 v0, s1
	ds_read_b32 v0, v0
	s_waitcnt lgkmcnt(1)
	v_cmp_ne_u32_e32 vcc, 0, v2
	s_cbranch_vccnz .LBB0_215
	s_add_u32 s4, s78, 0x80200
	s_addc_u32 s5, s79, 0
	s_add_u32 s6, s78, 0x80400
	s_addc_u32 s7, s79, 0
	s_add_u32 s8, s78, 0x80500
	s_addc_u32 s9, s79, 0
	s_add_u32 s10, s78, 0x80600
	s_addc_u32 s11, s79, 0
	s_add_u32 s16, s78, 0x80700
	s_addc_u32 s17, s79, 0
	s_add_u32 s18, s78, 0x80800
	s_addc_u32 s19, s79, 0
	s_add_u32 s20, s78, 0x80900
	s_addc_u32 s21, s79, 0
	s_add_u32 s22, s78, 0x80a00
	s_addc_u32 s23, s79, 0
	s_add_u32 s24, s78, 0x80b00
	s_addc_u32 s25, s79, 0
	s_add_u32 s26, s78, 0x80c00
	s_addc_u32 s27, s79, 0
	s_add_u32 s28, s78, 0x80d00
	s_addc_u32 s29, s79, 0
	s_add_u32 s30, s78, 0x80e00
	s_addc_u32 s31, s79, 0
	s_add_u32 s34, s78, 0x80f00
	s_addc_u32 s35, s79, 0
	s_add_u32 s36, s78, 0x81000
	s_addc_u32 s37, s79, 0
	s_add_u32 s38, s78, 0x81100
	s_addc_u32 s39, s79, 0
	s_add_u32 s40, s78, 0x81200
	v_readlane_b32 s1, v254, 1
	s_addc_u32 s41, s79, 0
	s_mul_i32 s1, s51, s1
	s_add_u32 s42, s78, 0x81300
	s_mul_i32 s1, s1, s50
	s_addc_u32 s43, s79, 0
	s_mov_b32 s12, 1
	v_mov_b32_e32 v16, 0
	s_branch .LBB0_203

.LBB0_741:
	s_waitcnt vmcnt(0)
	s_waitcnt lgkmcnt(0)
	s_barrier
	v_readfirstlane_b32 s98, v192
	s_nop 3
	s_lshr_b32 s98, s98, 6
	s_cmp_lg_u32 s98, 1
	s_cbranch_scc1 .Lxb_w1_2
	buffer_inv sc1
	s_waitcnt vmcnt(0)
.Lxb_w1_2:
	s_mov_b64 s[0:1], exec
	v_readlane_b32 s2, v254, 39
	v_readlane_b32 s3, v254, 40
	s_and_b64 s[2:3], s[0:1], s[2:3]
	s_mov_b64 exec, s[2:3]
	s_cbranch_execz .LBB0_793
	s_add_i32 s2, 0, 0x23ff0
	v_mov_b32_e32 v0, s2
	s_waitcnt vmcnt(0) expcnt(0) lgkmcnt(0)
	ds_read_b32 v2, v0
	s_add_i32 s2, 0, 0x23ff4
	v_mov_b32_e32 v0, s2
	ds_read_b32 v0, v0
	s_waitcnt lgkmcnt(1)
	v_cmp_ne_u32_e32 vcc, 0, v2
	s_cbranch_vccnz .LBB0_757
	v_readlane_b32 s2, v254, 1
	s_mul_i32 s44, s89, s2
	s_add_u32 s2, s78, 0x80200
	s_addc_u32 s3, s79, 0
	s_add_u32 s4, s78, 0x80400
	s_addc_u32 s5, s79, 0
	s_add_u32 s6, s78, 0x80500
	s_addc_u32 s7, s79, 0
	s_add_u32 s8, s78, 0x80600
	s_addc_u32 s9, s79, 0
	s_add_u32 s10, s78, 0x80700
	s_addc_u32 s11, s79, 0
	s_add_u32 s12, s78, 0x80800
	s_addc_u32 s13, s79, 0
	s_add_u32 s14, s78, 0x80900
	s_addc_u32 s15, s79, 0
	s_add_u32 s16, s78, 0x80a00
	s_addc_u32 s17, s79, 0
	s_add_u32 s18, s78, 0x80b00
	s_addc_u32 s19, s79, 0
	s_add_u32 s20, s78, 0x80c00
	s_addc_u32 s21, s79, 0
	s_add_u32 s22, s78, 0x80d00
	s_addc_u32 s23, s79, 0
	s_add_u32 s24, s78, 0x80e00
	s_addc_u32 s25, s79, 0
	s_add_u32 s26, s78, 0x80f00
	s_addc_u32 s27, s79, 0
	s_add_u32 s28, s78, 0x81000
	s_addc_u32 s29, s79, 0
	s_add_u32 s30, s78, 0x81100
	s_addc_u32 s31, s79, 0
	s_add_u32 s34, s78, 0x81200
	s_addc_u32 s35, s79, 0
	s_add_u32 s36, s78, 0x81300
	s_mul_i32 s44, s44, s88
	s_addc_u32 s37, s79, 0
	s_mov_b32 s45, 1
	v_mov_b32_e32 v16, 0
	s_branch .LBB0_745

.Lxb_w1_3:
	s_mov_b64 s[0:1], exec
	v_readlane_b32 s2, v254, 39
	v_readlane_b32 s3, v254, 40
	s_and_b64 s[2:3], s[0:1], s[2:3]
	s_mov_b64 exec, s[2:3]
	s_cbranch_execz .LBB0_903
	s_add_i32 s2, 0, 0x23ff0
	v_mov_b32_e32 v0, s2
	s_waitcnt vmcnt(0) expcnt(0) lgkmcnt(0)
	ds_read_b32 v2, v0
	s_add_i32 s2, 0, 0x23ff4
	v_mov_b32_e32 v0, s2
	ds_read_b32 v0, v0
	s_waitcnt lgkmcnt(1)
	v_cmp_ne_u32_e32 vcc, 0, v2
	s_cbranch_vccnz .LBB0_867
	v_readlane_b32 s2, v254, 1
	s_mul_i32 s33, s89, s2
	s_add_u32 s2, s78, 0x80200
	s_addc_u32 s3, s79, 0
	s_add_u32 s4, s78, 0x80400
	s_addc_u32 s5, s79, 0
	s_add_u32 s6, s78, 0x80500
	s_addc_u32 s7, s79, 0
	s_add_u32 s8, s78, 0x80600
	s_addc_u32 s9, s79, 0
	s_add_u32 s10, s78, 0x80700
	s_addc_u32 s11, s79, 0
	s_add_u32 s12, s78, 0x80800
	s_addc_u32 s13, s79, 0
	s_add_u32 s14, s78, 0x80900
	s_addc_u32 s15, s79, 0
	s_add_u32 s16, s78, 0x80a00
	s_addc_u32 s17, s79, 0
	s_add_u32 s18, s78, 0x80b00
	s_addc_u32 s19, s79, 0
	s_add_u32 s20, s78, 0x80c00
	s_addc_u32 s21, s79, 0
	s_add_u32 s22, s78, 0x80d00
	s_addc_u32 s23, s79, 0
	s_add_u32 s24, s78, 0x80e00
	s_addc_u32 s25, s79, 0
	s_add_u32 s26, s78, 0x80f00
	s_addc_u32 s27, s79, 0
	s_add_u32 s28, s78, 0x81000
	s_addc_u32 s29, s79, 0
	s_add_u32 s30, s78, 0x81100
	s_addc_u32 s31, s79, 0
	s_add_u32 s34, s78, 0x81200
	s_addc_u32 s35, s79, 0
	s_add_u32 s36, s78, 0x81300
	s_mul_i32 s33, s33, s88
	s_addc_u32 s37, s79, 0
	s_mov_b32 s44, 1
	v_mov_b32_e32 v16, 0
	s_branch .LBB0_855

.LBB0_920:
	s_or_b64 exec, exec, s[0:1]
	s_waitcnt vmcnt(0)
	s_barrier
	v_readfirstlane_b32 s98, v192
	s_nop 3
	s_lshr_b32 s98, s98, 6
	s_cmp_lg_u32 s98, 1
	s_cbranch_scc1 .Lxb_w1_4
	buffer_inv sc1
	s_waitcnt vmcnt(0)

.LBB0_1002:
	s_waitcnt vmcnt(0)
	s_waitcnt vmcnt(0)
	s_barrier
	v_readfirstlane_b32 s98, v192
	s_nop 3
	s_lshr_b32 s98, s98, 6
	s_cmp_lg_u32 s98, 1
	s_cbranch_scc1 .Lxb_w1_5
	buffer_inv sc1
	s_waitcnt vmcnt(0)
.Lxb_w1_5:
	s_mov_b64 s[2:3], exec
	v_readlane_b32 s4, v254, 39
	v_readlane_b32 s5, v254, 40
	s_and_b64 s[4:5], s[2:3], s[4:5]
	s_mov_b64 exec, s[4:5]
	s_cbranch_execz .LBB0_1054
	s_add_i32 s4, 0, 0x23ff0
	v_mov_b32_e32 v0, s4
	s_waitcnt vmcnt(0) expcnt(0) lgkmcnt(0)
	ds_read_b32 v2, v0
	s_add_i32 s4, 0, 0x23ff4
	v_mov_b32_e32 v0, s4
	ds_read_b32 v0, v0
	s_waitcnt lgkmcnt(1)
	v_cmp_ne_u32_e32 vcc, 0, v2
	s_cbranch_vccnz .LBB0_1018
	v_readlane_b32 s4, v254, 1
	s_mul_i32 s33, s89, s4
	s_add_u32 s4, s78, 0x80200
	s_addc_u32 s5, s79, 0
	s_add_u32 s6, s78, 0x80400
	s_addc_u32 s7, s79, 0
	s_add_u32 s8, s78, 0x80500
	s_addc_u32 s9, s79, 0
	s_add_u32 s10, s78, 0x80600
	s_addc_u32 s11, s79, 0
	s_add_u32 s12, s78, 0x80700
	s_addc_u32 s13, s79, 0
	s_add_u32 s14, s78, 0x80800
	s_addc_u32 s15, s79, 0
	s_add_u32 s16, s78, 0x80900
	s_addc_u32 s17, s79, 0
	s_add_u32 s18, s78, 0x80a00
	s_addc_u32 s19, s79, 0
	s_add_u32 s20, s78, 0x80b00
	s_addc_u32 s21, s79, 0
	s_add_u32 s22, s78, 0x80c00
	s_addc_u32 s23, s79, 0
	s_add_u32 s24, s78, 0x80d00
	s_addc_u32 s25, s79, 0
	s_add_u32 s26, s78, 0x80e00
	s_addc_u32 s27, s79, 0
	s_add_u32 s28, s78, 0x80f00
	s_addc_u32 s29, s79, 0
	s_add_u32 s30, s78, 0x81000
	s_addc_u32 s31, s79, 0
	s_add_u32 s34, s78, 0x81100
	s_addc_u32 s35, s79, 0
	s_add_u32 s36, s78, 0x81200
	s_addc_u32 s37, s79, 0
	s_add_u32 s38, s78, 0x81300
	s_mul_i32 s33, s33, s88
	s_addc_u32 s39, s79, 0
	s_mov_b32 s47, 1
	v_mov_b32_e32 v16, 0
	s_branch .LBB0_1006

.Lxb_w1_6:
	s_mov_b64 s[0:1], exec
	v_readlane_b32 s2, v254, 39
	v_readlane_b32 s3, v254, 40
	s_and_b64 s[2:3], s[0:1], s[2:3]
	s_mov_b64 exec, s[2:3]
	s_cbranch_execz .LBB0_1148
	s_add_i32 s2, 0, 0x23ff0
	v_mov_b32_e32 v0, s2
	s_waitcnt vmcnt(0) expcnt(0) lgkmcnt(0)
	ds_read_b32 v2, v0
	s_add_i32 s2, 0, 0x23ff4
	v_mov_b32_e32 v0, s2
	ds_read_b32 v0, v0
	s_waitcnt lgkmcnt(1)
	v_cmp_ne_u32_e32 vcc, 0, v2
	s_cbranch_vccnz .LBB0_1112
	v_readlane_b32 s2, v254, 1
	s_mul_i32 s33, s89, s2
	s_add_u32 s2, s78, 0x80200
	s_addc_u32 s3, s79, 0
	s_add_u32 s4, s78, 0x80400
	s_addc_u32 s5, s79, 0
	s_add_u32 s6, s78, 0x80500
	s_addc_u32 s7, s79, 0
	s_add_u32 s8, s78, 0x80600
	s_addc_u32 s9, s79, 0
	s_add_u32 s10, s78, 0x80700
	s_addc_u32 s11, s79, 0
	s_add_u32 s14, s78, 0x80800
	s_addc_u32 s15, s79, 0
	s_add_u32 s16, s78, 0x80900
	s_addc_u32 s17, s79, 0
	s_add_u32 s18, s78, 0x80a00
	s_addc_u32 s19, s79, 0
	s_add_u32 s20, s78, 0x80b00
	s_addc_u32 s21, s79, 0
	s_add_u32 s22, s78, 0x80c00
	s_addc_u32 s23, s79, 0
	s_add_u32 s24, s78, 0x80d00
	s_addc_u32 s25, s79, 0
	s_add_u32 s26, s78, 0x80e00
	s_addc_u32 s27, s79, 0
	s_add_u32 s28, s78, 0x80f00
	s_addc_u32 s29, s79, 0
	s_add_u32 s30, s78, 0x81000
	s_addc_u32 s31, s79, 0
	s_add_u32 s34, s78, 0x81100
	s_addc_u32 s35, s79, 0
	s_add_u32 s36, s78, 0x81200
	s_addc_u32 s37, s79, 0
	s_add_u32 s38, s78, 0x81300
	s_mul_i32 s33, s33, s88
	s_addc_u32 s39, s79, 0
	s_mov_b32 s47, 1
	v_mov_b32_e32 v16, 0
	s_branch .LBB0_1100

.Lxb_w1_7:
	s_mov_b64 s[0:1], exec
	v_readlane_b32 s2, v254, 39
	v_readlane_b32 s3, v254, 40
	s_and_b64 s[2:3], s[0:1], s[2:3]
	s_mov_b64 exec, s[2:3]
	s_cbranch_execz .LBB0_1203
	s_add_i32 s2, 0, 0x23ff0
	v_mov_b32_e32 v0, s2
	s_waitcnt vmcnt(0) expcnt(0) lgkmcnt(0)
	ds_read_b32 v2, v0
	s_add_i32 s2, 0, 0x23ff4
	v_mov_b32_e32 v0, s2
	ds_read_b32 v0, v0
	s_waitcnt lgkmcnt(1)
	v_cmp_ne_u32_e32 vcc, 0, v2
	s_cbranch_vccnz .LBB0_1167
	v_readlane_b32 s2, v254, 1
	s_mul_i32 s33, s89, s2
	s_add_u32 s2, s78, 0x80200
	s_addc_u32 s3, s79, 0
	s_add_u32 s4, s78, 0x80400
	s_addc_u32 s5, s79, 0
	s_add_u32 s6, s78, 0x80500
	s_addc_u32 s7, s79, 0
	s_add_u32 s8, s78, 0x80600
	s_addc_u32 s9, s79, 0
	s_add_u32 s10, s78, 0x80700
	s_addc_u32 s11, s79, 0
	s_add_u32 s14, s78, 0x80800
	s_addc_u32 s15, s79, 0
	s_add_u32 s16, s78, 0x80900
	s_addc_u32 s17, s79, 0
	s_add_u32 s18, s78, 0x80a00
	s_addc_u32 s19, s79, 0
	s_add_u32 s20, s78, 0x80b00
	s_addc_u32 s21, s79, 0
	s_add_u32 s22, s78, 0x80c00
	s_addc_u32 s23, s79, 0
	s_add_u32 s24, s78, 0x80d00
	s_addc_u32 s25, s79, 0
	s_add_u32 s26, s78, 0x80e00
	s_addc_u32 s27, s79, 0
	s_add_u32 s28, s78, 0x80f00
	s_addc_u32 s29, s79, 0
	s_add_u32 s30, s78, 0x81000
	s_addc_u32 s31, s79, 0
	s_add_u32 s34, s78, 0x81100
	s_addc_u32 s35, s79, 0
	s_add_u32 s36, s78, 0x81200
	s_addc_u32 s37, s79, 0
	s_add_u32 s38, s78, 0x81300
	s_mul_i32 s33, s33, s88
	s_addc_u32 s39, s79, 0
	s_mov_b32 s46, 1
	v_mov_b32_e32 v16, 0
	s_branch .LBB0_1155

.Lxb_w1_8:
	s_mov_b64 s[0:1], exec
	v_readlane_b32 s2, v254, 39
	v_readlane_b32 s3, v254, 40
	s_and_b64 s[2:3], s[0:1], s[2:3]
	s_mov_b64 exec, s[2:3]
	s_cbranch_execz .LBB0_1278
	s_add_i32 s2, 0, 0x23ff0
	v_mov_b32_e32 v0, s2
	s_waitcnt vmcnt(0) expcnt(0) lgkmcnt(0)
	ds_read_b32 v2, v0
	s_add_i32 s2, 0, 0x23ff4
	v_mov_b32_e32 v0, s2
	ds_read_b32 v0, v0
	s_waitcnt lgkmcnt(1)
	v_cmp_ne_u32_e32 vcc, 0, v2
	s_cbranch_vccnz .LBB0_1242
	v_readlane_b32 s2, v254, 1
	s_mul_i32 s33, s89, s2
	s_add_u32 s2, s78, 0x80200
	s_addc_u32 s3, s79, 0
	s_add_u32 s4, s78, 0x80400
	s_addc_u32 s5, s79, 0
	s_add_u32 s6, s78, 0x80500
	s_addc_u32 s7, s79, 0
	s_add_u32 s8, s78, 0x80600
	s_addc_u32 s9, s79, 0
	s_add_u32 s10, s78, 0x80700
	s_addc_u32 s11, s79, 0
	s_add_u32 s16, s78, 0x80800
	s_addc_u32 s17, s79, 0
	s_add_u32 s18, s78, 0x80900
	s_addc_u32 s19, s79, 0
	s_add_u32 s20, s78, 0x80a00
	s_addc_u32 s21, s79, 0
	s_add_u32 s22, s78, 0x80b00
	s_addc_u32 s23, s79, 0
	s_add_u32 s24, s78, 0x80c00
	s_addc_u32 s25, s79, 0
	s_add_u32 s26, s78, 0x80d00
	s_addc_u32 s27, s79, 0
	s_add_u32 s28, s78, 0x80e00
	s_addc_u32 s29, s79, 0
	s_add_u32 s30, s78, 0x80f00
	s_addc_u32 s31, s79, 0
	s_add_u32 s34, s78, 0x81000
	s_addc_u32 s35, s79, 0
	s_add_u32 s36, s78, 0x81100
	s_addc_u32 s37, s79, 0
	s_add_u32 s38, s78, 0x81200
	s_addc_u32 s39, s79, 0
	s_add_u32 s40, s78, 0x81300
	s_mul_i32 s33, s33, s88
	s_addc_u32 s41, s79, 0
	s_mov_b32 s48, 1
	v_mov_b32_e32 v16, 0
	s_branch .LBB0_1230
